# v51 + prologue row pass: loop-invariant gate bias loaded once, counted wait at loop head
# baseline (speedup 1.0000x reference)
; DI void prologue_phase(const Params& p, unsigned char* smem) {
;     ...
;     {
;         float* wg = (float*)smem;
;         __syncthreads();
;         for (int i = tid; i < 8192; i += 512) { const int k = i >> 3, j = i & 7; wg[i] = p.ab_w_in[(size_t)k * 6152 + 4096 + j] * p.norm_mix[k]; }
;         __syncthreads();
;         bf16_t* hn = (bf16_t*)(p.ws + OFF_HB);
;         float* LI = (float*)(p.ws + OFF_LI); float* LF = (float*)(p.ws + OFF_LF);
;         const int rstep = gridDim.x * 8;
;         int r = blockIdx.x * 8 + wid;
;         f32x4 nx[4];
;         auto load_row = [&](int rr) __attribute__((always_inline)) {
;             const float* s = rr < MR ? p.x + (size_t)rr * 1024 : p.meta + (size_t)(rr - MR) * 1024;
; #pragma unroll
;             for (int i = 0; i < 4; ++i) nx[i] = *(const f32x4*)(s + i * 256 + lane * 4);
;         };
;         if (r < MR + 16) load_row(r);
;         for (; r < MR + 16; r += rstep) {
;             f32x4 v[4];
; #pragma unroll
;             for (int i = 0; i < 4; ++i) v[i] = nx[i];
;             if (r + rstep < MR + 16) load_row(r + rstep);
.LBB0_84:
	s_or_b64 exec, exec, s[4:5]
	s_add_u32 s80, s54, 0x3880000
	v_ashrrev_i32_e32 v146, 6, v16
	s_addc_u32 s81, s55, 0
	s_lshl_b32 s85, s84, 3
	v_readlane_b32 s0, v230, 0
	v_add_u32_e32 v160, s85, v146
	s_mov_b32 s2, 0x8010
	s_lshl_b32 s86, s0, 3
	v_cmp_gt_i32_e32 vcc, s2, v160
	s_waitcnt lgkmcnt(0)
	s_barrier
	v_readlane_b32 s1, v230, 1
	s_and_saveexec_b64 s[12:13], vcc
	s_cbranch_execz .LBB0_94
	s_mov_b32 s3, 0x8000
	v_add_u32_e32 v0, 0xffff8000, v160
	v_ashrrev_i32_e32 v161, 31, v160
	v_cmp_gt_i32_e32 vcc, s3, v160
	v_mov_b32_e32 v2, s59
	v_mov_b32_e32 v3, s57
	v_cndmask_b32_e32 v1, 0, v161, vcc
	v_cndmask_b32_e32 v0, v0, v160, vcc
	v_cndmask_b32_e32 v3, v2, v3, vcc
	v_mov_b32_e32 v2, s58
	v_mov_b32_e32 v4, s56
	v_cndmask_b32_e32 v2, v2, v4, vcc
	v_lshlrev_b64 v[0:1], 12, v[0:1]
	v_mov_b32_e32 v163, 0
	v_lshl_add_u64 v[0:1], v[2:3], 0, v[0:1]
	v_lshlrev_b32_e32 v162, 4, v145
	v_lshl_add_u64 v[12:13], v[0:1], 0, v[162:163]
	global_load_dwordx4 v[0:3], v[12:13], off
	global_load_dwordx4 v[4:7], v[12:13], off offset:1024
	global_load_dwordx4 v[8:11], v[12:13], off offset:2048
	s_nop 0
	global_load_dwordx4 v[12:15], v[12:13], off offset:3072
	v_mbcnt_hi_u32_b32 v17, -1, v175
	v_and_b32_e32 v19, 64, v17
	v_add_u32_e32 v19, 64, v19
	v_xor_b32_e32 v20, 32, v17
	v_cmp_lt_i32_e32 vcc, v20, v19
	v_lshl_add_u32 v140, v145, 7, 0
	v_cmp_eq_u32_e64 s[6:7], 0, v18
	v_cndmask_b32_e32 v20, v17, v20, vcc
	v_lshlrev_b32_e32 v176, 2, v20
	v_xor_b32_e32 v20, 16, v17
	v_cmp_lt_i32_e32 vcc, v20, v19
	v_lshrrev_b32_e32 v147, 3, v145
	v_lshlrev_b32_e32 v162, 2, v147
	v_cndmask_b32_e32 v20, v17, v20, vcc
	v_lshlrev_b32_e32 v177, 2, v20
	v_xor_b32_e32 v20, 8, v17
	v_cmp_lt_i32_e32 vcc, v20, v19
	v_lshl_or_b32 v147, s84, 5, v147
	v_lshl_add_u32 v166, v146, 2, v147
	v_cndmask_b32_e32 v20, v17, v20, vcc
	v_lshlrev_b32_e32 v179, 2, v20
	v_xor_b32_e32 v20, 4, v17
	v_cmp_lt_i32_e32 vcc, v20, v19
	v_readlane_b32 s14, v230, 0
	v_lshlrev_b64 v[146:147], 11, v[160:161]
	v_cndmask_b32_e32 v20, v17, v20, vcc
	v_lshlrev_b32_e32 v180, 2, v20
	v_xor_b32_e32 v20, 2, v17
	v_cmp_lt_i32_e32 vcc, v20, v19
	v_readlane_b32 s15, v230, 1
	v_lshl_or_b32 v146, v145, 3, v146
	v_cndmask_b32_e32 v20, v17, v20, vcc
	v_lshlrev_b32_e32 v181, 2, v20
	v_xor_b32_e32 v20, 1, v17
	v_cmp_lt_i32_e32 vcc, v20, v19
	s_lshl_b32 s22, s14, 5
	v_lshl_add_u64 v[146:147], s[54:55], 0, v[146:147]
	v_cndmask_b32_e32 v17, v17, v20, vcc
	v_lshlrev_b32_e32 v182, 2, v17
	v_and_b32_e32 v17, 32, v16
	v_cmp_eq_u32_e64 s[0:1], 0, v17
	v_and_b32_e32 v17, 16, v16
	v_and_b32_e32 v16, 8, v16
	v_cmp_eq_u32_e64 s[10:11], 0, v17
	v_cmp_eq_u32_e64 s[4:5], 0, v16
	ds_read_b128 v[16:19], v140
	ds_read_b128 v[20:23], v140 offset:16
	ds_read_b128 v[24:27], v140 offset:32
	ds_read_b128 v[28:31], v140 offset:48
	ds_read_b128 v[32:35], v140 offset:64
	ds_read_b128 v[36:39], v140 offset:80
	ds_read_b128 v[40:43], v140 offset:96
	ds_read_b128 v[44:47], v140 offset:112
	ds_read_b128 v[48:51], v140 offset:8192
	ds_read_b128 v[52:55], v140 offset:8208
	ds_read_b128 v[56:59], v140 offset:8224
	ds_read_b128 v[60:63], v140 offset:8240
	ds_read_b128 v[64:67], v140 offset:8256
	ds_read_b128 v[68:71], v140 offset:8272
	ds_read_b128 v[72:75], v140 offset:8288
	ds_read_b128 v[76:79], v140 offset:8304
	ds_read_b128 v[80:83], v140 offset:16384
	ds_read_b128 v[84:87], v140 offset:16400
	ds_read_b128 v[88:91], v140 offset:16416
	ds_read_b128 v[92:95], v140 offset:16432
	ds_read_b128 v[96:99], v140 offset:16448
	ds_read_b128 v[100:103], v140 offset:16464
	ds_read_b128 v[104:107], v140 offset:16480
	ds_read_b128 v[108:111], v140 offset:16496
	ds_read_b128 v[112:115], v140 offset:24576
	ds_read_b128 v[116:119], v140 offset:24592
	ds_read_b128 v[120:123], v140 offset:24608
	ds_read_b128 v[124:127], v140 offset:24624
	ds_read_b128 v[128:131], v140 offset:24640
	ds_read_b128 v[132:135], v140 offset:24656
	ds_read_b128 v[136:139], v140 offset:24672
	ds_read_b128 v[140:143], v140 offset:24688
	s_mov_b64 s[14:15], 0x3ac7b00
	s_ashr_i32 s87, s86, 31
	v_add_u32_e32 v170, s86, v160
	v_cmp_lt_u32_e64 s[8:9], 31, v145
	v_lshl_add_u64 v[164:165], s[68:69], 0, v[162:163]
	v_lshl_add_u64 v[168:169], v[146:147], 0, s[14:15]
	s_lshl_b64 s[14:15], s[86:87], 11
	v_ashrrev_i32_e32 v171, 31, v170
	s_mov_b64 s[16:17], 0
	v_lshlrev_b32_e32 v162, 2, v144
	v_mov_b32_e32 v161, 0x358637bd
	s_mov_b32 s23, 0x800000
	s_mov_b32 s24, 0xbfb8aa3b
	s_mov_b32 s25, 0x3f2aaaab
	v_mov_b32_e32 v183, 0x3ecc95a3
	s_mov_b32 s26, 0x3f317218
	s_mov_b32 s27, 0x7f800000
	s_mov_b32 s28, 0x33800000
	s_mov_b32 s29, 0x800f
	v_mov_b32_e32 v172, 0x3f317218
	v_mov_b32_e32 v184, 0x7f800000
	v_mov_b32_e32 v185, 0x7fc00000
	v_mov_b32_e32 v186, 0xff800000
	global_load_dword v204, v[164:165], off
	s_waitcnt vmcnt(0)
	s_branch .LBB0_87
.LBB0_86:
	s_or_b64 exec, exec, s[18:19]
	v_add_u32_e32 v160, s86, v160
	v_cmp_lt_i32_e32 vcc, s29, v160
	v_add_u32_e32 v166, s22, v166
	v_lshl_add_u64 v[168:169], v[168:169], 0, s[14:15]
	s_or_b64 s[16:17], vcc, s[16:17]
	v_lshl_add_u64 v[170:171], v[170:171], 0, s[86:87]
	s_andn2_b64 exec, exec, s[16:17]
	s_cbranch_execz .LBB0_94
	s_waitcnt vmcnt(4)
.LBB0_87:
	v_mov_b64_e32 v[146:147], v[14:15]
	s_waitcnt lgkmcnt(0)
	v_mov_b64_e32 v[150:151], v[10:11]
	v_mov_b64_e32 v[154:155], v[6:7]
	v_mov_b64_e32 v[158:159], v[2:3]
	v_mov_b64_e32 v[144:145], v[12:13]
	v_mov_b64_e32 v[148:149], v[8:9]
	v_mov_b64_e32 v[152:153], v[4:5]
	v_mov_b64_e32 v[156:157], v[0:1]
	v_cmp_gt_i32_e32 vcc, s2, v170
	s_and_saveexec_b64 s[18:19], vcc
	s_cbranch_execz .LBB0_89
	v_add_u32_e32 v0, 0xffff8000, v170
	v_cmp_gt_i32_e32 vcc, s3, v170
	v_mov_b32_e32 v2, s59
	v_mov_b32_e32 v3, s57
	v_cndmask_b32_e32 v1, 0, v171, vcc
	v_cndmask_b32_e32 v0, v0, v170, vcc
	v_cndmask_b32_e32 v3, v2, v3, vcc
	v_mov_b32_e32 v2, s58
	v_mov_b32_e32 v4, s56
	v_cndmask_b32_e32 v2, v2, v4, vcc
	v_lshlrev_b64 v[0:1], 12, v[0:1]
	v_lshl_add_u64 v[0:1], v[2:3], 0, v[0:1]
	v_lshl_add_u64 v[12:13], v[0:1], 0, v[162:163]
	global_load_dwordx4 v[0:3], v[12:13], off
	global_load_dwordx4 v[4:7], v[12:13], off offset:1024
	global_load_dwordx4 v[8:11], v[12:13], off offset:2048
	s_nop 0
	global_load_dwordx4 v[12:15], v[12:13], off offset:3072
; DI void prologue_phase(const Params& p, unsigned char* smem) {
;     ...
;             f32x4 v[4];
; #pragma unroll
;             for (int i = 0; i < 4; ++i) v[i] = nx[i];
;             if (r + rstep < MR + 16) load_row(r + rstep);
;             float sq = 0.f;
; #pragma unroll
;             for (int i = 0; i < 4; ++i) sq += v[i][0] * v[i][0] + v[i][1] * v[i][1] + v[i][2] * v[i][2] + v[i][3] * v[i][3];
;             float g[8];
; #pragma unroll
;             for (int j = 0; j < 8; ++j) g[j] = 0.f;
; #pragma unroll
;             for (int i = 0; i < 4; ++i) {
; #pragma unroll
;                 for (int e = 0; e < 4; ++e) {
;                     const float* wr_ = wg + (i * 256 + lane * 4 + e) * 8;
;                     const f32x4 w0 = *(const f32x4*)wr_, w1 = *(const f32x4*)(wr_ + 4);
;                     g[0] += v[i][e] * w0[0]; g[1] += v[i][e] * w0[1]; g[2] += v[i][e] * w0[2]; g[3] += v[i][e] * w0[3];
;                     g[4] += v[i][e] * w1[0]; g[5] += v[i][e] * w1[1]; g[6] += v[i][e] * w1[2]; g[7] += v[i][e] * w1[3];
;                 }
;             }
;             sq = wave_sum(sq);
;             const float rstd = rsqrtf(sq * (1.0f / 1024.0f) + EPS);
; #pragma unroll
;             for (int i = 0; i < 4; ++i) {
;                 u32x2 w; w.x = pk2(v[i][0] * rstd, v[i][1] * rstd); w.y = pk2(v[i][2] * rstd, v[i][3] * rstd);
;                 *(u32x2*)(hn + (size_t)r * 1024 + i * 256 + lane * 4) = w;
;             }
;             float h4[4], h2[2], h1;
;             {
;                 const bool up = (lane & 32) != 0;
; #pragma unroll
;                 for (int j = 0; j < 4; ++j) { const float mine = up ? g[4 + j] : g[j], send = up ? g[j] : g[4 + j]; h4[j] = mine + __shfl_xor(send, 32); }
;             }
;             {
;                 const bool up = (lane & 16) != 0;
; #pragma unroll
;                 for (int j = 0; j < 2; ++j) { const float mine = up ? h4[2 + j] : h4[j], send = up ? h4[j] : h4[2 + j]; h2[j] = mine + __shfl_xor(send, 16); }
;             }
;             {
;                 const bool up = (lane & 8) != 0;
;                 const float mine = up ? h2[1] : h2[0], send = up ? h2[0] : h2[1];
;                 h1 = mine + __shfl_xor(send, 8);
;             }
;             h1 += __shfl_xor(h1, 4); h1 += __shfl_xor(h1, 2); h1 += __shfl_xor(h1, 1);
.LBB0_89:
	s_or_b64 exec, exec, s[18:19]
	v_mov_b32_e32 v188, v157
	v_mov_b32_e32 v189, v153
	v_pk_mul_f32 v[188:189], v[188:189], v[188:189]
	v_mov_b32_e32 v194, v156
	v_mov_b32_e32 v195, v152
	v_mov_b32_e32 v198, v149
	v_mov_b32_e32 v199, v145
	v_mov_b32_e32 v190, v158
	v_mov_b32_e32 v191, v154
	v_mov_b32_e32 v196, v148
	v_mov_b32_e32 v197, v144
	v_pk_mul_f32 v[198:199], v[198:199], v[198:199]
	v_pk_fma_f32 v[188:189], v[194:195], v[194:195], v[188:189]
	v_mov_b32_e32 v192, v159
	v_mov_b32_e32 v193, v155
	v_mov_b32_e32 v200, v150
	v_mov_b32_e32 v201, v146
	v_pk_fma_f32 v[196:197], v[196:197], v[196:197], v[198:199]
	v_pk_fma_f32 v[188:189], v[190:191], v[190:191], v[188:189]
	v_mov_b32_e32 v202, v151
	v_mov_b32_e32 v203, v147
	v_pk_fma_f32 v[196:197], v[200:201], v[200:201], v[196:197]
	v_pk_fma_f32 v[188:189], v[192:193], v[192:193], v[188:189]
	v_pk_fma_f32 v[196:197], v[202:203], v[202:203], v[196:197]
	v_add_f32_e32 v174, v188, v189
	v_add_f32_e32 v174, v174, v196
	v_add_f32_e32 v174, v174, v197
	ds_bpermute_b32 v188, v176, v174
	s_waitcnt lgkmcnt(14)
	v_fma_f32 v167, v156, v16, 0
	v_fma_f32 v191, v156, v20, 0
	v_fmac_f32_e32 v167, v157, v24
	v_fmac_f32_e32 v191, v157, v28
	s_waitcnt lgkmcnt(0)
	v_add_f32_e32 v174, v174, v188
	ds_bpermute_b32 v188, v177, v174
	v_fmac_f32_e32 v167, v158, v32
	v_fmac_f32_e32 v191, v158, v36
	v_fmac_f32_e32 v167, v159, v40
	v_fmac_f32_e32 v191, v159, v44
	s_waitcnt lgkmcnt(0)
	v_add_f32_e32 v174, v174, v188
	ds_bpermute_b32 v188, v179, v174
	v_fma_f32 v173, v156, v17, 0
	v_fma_f32 v192, v156, v21, 0
	v_fmac_f32_e32 v167, v152, v48
	v_fmac_f32_e32 v191, v152, v52
	s_waitcnt lgkmcnt(0)
	v_add_f32_e32 v174, v174, v188
	ds_bpermute_b32 v188, v180, v174
	v_fma_f32 v187, v156, v18, 0
	v_fma_f32 v193, v156, v22, 0
	v_fmac_f32_e32 v173, v157, v25
	v_fmac_f32_e32 v192, v157, v29
	s_waitcnt lgkmcnt(0)
	v_add_f32_e32 v174, v174, v188
	ds_bpermute_b32 v188, v181, v174
	v_fmac_f32_e32 v167, v153, v56
	v_fmac_f32_e32 v191, v153, v60
	v_fma_f32 v190, v156, v19, 0
	v_fma_f32 v194, v156, v23, 0
	s_waitcnt lgkmcnt(0)
	v_add_f32_e32 v174, v174, v188
	ds_bpermute_b32 v188, v182, v174
	v_fmac_f32_e32 v187, v157, v26
	v_fmac_f32_e32 v193, v157, v30
	v_fmac_f32_e32 v173, v158, v33
	v_fmac_f32_e32 v192, v158, v37
	v_fmac_f32_e32 v167, v154, v64
	v_fmac_f32_e32 v191, v154, v68
	v_fmac_f32_e32 v190, v157, v27
	v_fmac_f32_e32 v194, v157, v31
	v_fmac_f32_e32 v187, v158, v34
	v_fmac_f32_e32 v193, v158, v38
	v_fmac_f32_e32 v173, v159, v41
	v_fmac_f32_e32 v192, v159, v45
	v_fmac_f32_e32 v167, v155, v72
	v_fmac_f32_e32 v191, v155, v76
	s_waitcnt lgkmcnt(0)
	v_add_f32_e32 v174, v174, v188
	v_fmac_f32_e32 v190, v158, v35
	v_fmac_f32_e32 v194, v158, v39
	v_fmac_f32_e32 v187, v159, v42
	v_fmac_f32_e32 v193, v159, v46
	v_fmac_f32_e32 v173, v152, v49
	v_fmac_f32_e32 v192, v152, v53
	v_fmac_f32_e32 v167, v148, v80
	v_fmac_f32_e32 v191, v148, v84
	v_fmamk_f32 v174, v174, 0x3a800000, v161
	v_fmac_f32_e32 v190, v159, v43
	v_fmac_f32_e32 v194, v159, v47
	v_fmac_f32_e32 v187, v152, v50
	v_fmac_f32_e32 v193, v152, v54
	v_fmac_f32_e32 v173, v153, v57
	v_fmac_f32_e32 v192, v153, v61
	v_fmac_f32_e32 v167, v149, v88
	v_fmac_f32_e32 v191, v149, v92
	v_mul_f32_e32 v188, 0x4b800000, v174
	v_cmp_gt_f32_e32 vcc, s23, v174
	v_fmac_f32_e32 v190, v152, v51
	v_fmac_f32_e32 v194, v152, v55
	v_fmac_f32_e32 v187, v153, v58
	v_fmac_f32_e32 v193, v153, v62
	v_fmac_f32_e32 v173, v154, v65
	v_fmac_f32_e32 v192, v154, v69
	v_fmac_f32_e32 v167, v150, v96
	v_fmac_f32_e32 v191, v150, v100
	v_cndmask_b32_e32 v174, v174, v188, vcc
	v_fmac_f32_e32 v190, v153, v59
	v_fmac_f32_e32 v194, v153, v63
	v_fmac_f32_e32 v187, v154, v66
	v_fmac_f32_e32 v193, v154, v70
	v_fmac_f32_e32 v173, v155, v73
	v_fmac_f32_e32 v192, v155, v77
	v_fmac_f32_e32 v167, v151, v104
	v_fmac_f32_e32 v191, v151, v108
	v_rsq_f32_e32 v174, v174
	v_fmac_f32_e32 v190, v154, v67
	v_fmac_f32_e32 v194, v154, v71
	v_fmac_f32_e32 v187, v155, v74
	v_fmac_f32_e32 v193, v155, v78
	v_fmac_f32_e32 v173, v148, v81
	v_fmac_f32_e32 v192, v148, v85
	v_fmac_f32_e32 v167, v144, v112
	v_fmac_f32_e32 v191, v144, v116
	v_fmac_f32_e32 v190, v155, v75
	v_fmac_f32_e32 v194, v155, v79
	v_fmac_f32_e32 v187, v148, v82
	v_fmac_f32_e32 v193, v148, v86
	v_fmac_f32_e32 v173, v149, v89
	v_fmac_f32_e32 v192, v149, v93
	v_fmac_f32_e32 v167, v145, v120
	v_fmac_f32_e32 v191, v145, v124
	v_fmac_f32_e32 v190, v148, v83
	v_fmac_f32_e32 v194, v148, v87
	v_fmac_f32_e32 v187, v149, v90
	v_fmac_f32_e32 v193, v149, v94
	v_fmac_f32_e32 v173, v150, v97
	v_fmac_f32_e32 v192, v150, v101
	v_fmac_f32_e32 v167, v146, v128
	v_fmac_f32_e32 v191, v146, v132
	v_fmac_f32_e32 v190, v149, v91
	v_fmac_f32_e32 v194, v149, v95
	v_fmac_f32_e32 v187, v150, v98
	v_fmac_f32_e32 v193, v150, v102
	v_fmac_f32_e32 v173, v151, v105
	v_fmac_f32_e32 v192, v151, v109
	v_fmac_f32_e32 v167, v147, v136
	v_fmac_f32_e32 v191, v147, v140
	v_mul_f32_e32 v188, 0x45800000, v174
	v_fmac_f32_e32 v190, v150, v99
	v_fmac_f32_e32 v194, v150, v103
	v_fmac_f32_e32 v187, v151, v106
	v_fmac_f32_e32 v193, v151, v110
	v_fmac_f32_e32 v173, v144, v113
	v_fmac_f32_e32 v192, v144, v117
	v_cndmask_b32_e32 v174, v174, v188, vcc
	v_cndmask_b32_e64 v188, v167, v191, s[0:1]
	v_fmac_f32_e32 v190, v151, v107
	v_fmac_f32_e32 v194, v151, v111
	v_fmac_f32_e32 v187, v144, v114
	v_fmac_f32_e32 v193, v144, v118
	v_fmac_f32_e32 v173, v145, v121
	v_fmac_f32_e32 v192, v145, v125
	ds_bpermute_b32 v188, v176, v188
	v_fmac_f32_e32 v190, v144, v115
	v_fmac_f32_e32 v194, v144, v119
	v_fmac_f32_e32 v187, v145, v122
	v_fmac_f32_e32 v193, v145, v126
	v_fmac_f32_e32 v173, v146, v129
	v_fmac_f32_e32 v192, v146, v133
	v_fmac_f32_e32 v190, v145, v123
	v_fmac_f32_e32 v194, v145, v127
	v_fmac_f32_e32 v187, v146, v130
	v_fmac_f32_e32 v193, v146, v134
	v_fmac_f32_e32 v173, v147, v137
	v_fmac_f32_e32 v192, v147, v141
	v_pk_mul_f32 v[156:157], v[156:157], v[174:175] op_sel_hi:[1,0]
	v_pk_mul_f32 v[158:159], v[158:159], v[174:175] op_sel_hi:[1,0]
	v_fmac_f32_e32 v190, v146, v131
	v_fmac_f32_e32 v194, v146, v135
	v_fmac_f32_e32 v187, v147, v138
	v_fmac_f32_e32 v193, v147, v142
	v_cvt_pk_bf16_f32 v156, v156, v157
	v_cvt_pk_bf16_f32 v157, v158, v159
	v_cndmask_b32_e64 v158, v191, v167, s[0:1]
	v_cndmask_b32_e64 v167, v173, v192, s[0:1]
	v_fmac_f32_e32 v190, v147, v139
	v_fmac_f32_e32 v194, v147, v143
	v_cndmask_b32_e64 v159, v192, v173, s[0:1]
	ds_bpermute_b32 v167, v176, v167
	v_cndmask_b32_e64 v173, v187, v193, s[0:1]
	s_waitcnt lgkmcnt(1)
; DI unsigned pk2(float a, float b) { f32x2 v = {a, b}; hbf2 r = __builtin_convertvector(v, hbf2); return __builtin_bit_cast(unsigned, r); }
; DI void prologue_phase(const Params& p, unsigned char* smem) {
;     ...
;             for (int i = 0; i < 4; ++i) {
;                 u32x2 w; w.x = pk2(v[i][0] * rstd, v[i][1] * rstd); w.y = pk2(v[i][2] * rstd, v[i][3] * rstd);
;                 *(u32x2*)(hn + (size_t)r * 1024 + i * 256 + lane * 4) = w;
;             }
;             float h4[4], h2[2], h1;
;             {
;                 const bool up = (lane & 32) != 0;
; #pragma unroll
;                 for (int j = 0; j < 4; ++j) { const float mine = up ? g[4 + j] : g[j], send = up ? g[j] : g[4 + j]; h4[j] = mine + __shfl_xor(send, 32); }
;             }
;             {
;                 const bool up = (lane & 16) != 0;
; #pragma unroll
;                 for (int j = 0; j < 2; ++j) { const float mine = up ? h4[2 + j] : h4[j], send = up ? h4[j] : h4[2 + j]; h2[j] = mine + __shfl_xor(send, 16); }
;             }
;             {
;                 const bool up = (lane & 8) != 0;
;                 const float mine = up ? h2[1] : h2[0], send = up ? h2[0] : h2[1];
;                 h1 = mine + __shfl_xor(send, 8);
;             }
;             h1 += __shfl_xor(h1, 4); h1 += __shfl_xor(h1, 2); h1 += __shfl_xor(h1, 1);
;             if ((lane & 7) == 0) {
;                 const int gi = ((lane >> 5) & 1) * 4 + ((lane >> 4) & 1) * 2 + ((lane >> 3) & 1);
;                 const float pre = h1 * rstd + p.ab_if_bias[gi];
;                 if (gi < 4) LI[r * 4 + gi] = pre;
	v_add_f32_e32 v158, v158, v188
	ds_bpermute_b32 v173, v176, v173
	v_cndmask_b32_e64 v188, v190, v194, s[0:1]
	ds_bpermute_b32 v188, v176, v188
	s_waitcnt lgkmcnt(2)
	v_add_f32_e32 v159, v159, v167
	v_cndmask_b32_e64 v167, v193, v187, s[0:1]
	s_waitcnt lgkmcnt(1)
	v_add_f32_e32 v167, v167, v173
	v_cndmask_b32_e64 v173, v194, v190, s[0:1]
	s_waitcnt lgkmcnt(0)
	v_add_f32_e32 v173, v173, v188
	v_cndmask_b32_e64 v187, v158, v167, s[10:11]
	v_cndmask_b32_e64 v188, v159, v173, s[10:11]
	ds_bpermute_b32 v187, v177, v187
	ds_bpermute_b32 v188, v177, v188
	global_store_dwordx2 v[168:169], v[156:157], off
	v_cndmask_b32_e64 v156, v167, v158, s[10:11]
	v_cndmask_b32_e64 v157, v173, v159, s[10:11]
	s_waitcnt lgkmcnt(1)
	v_add_f32_e32 v156, v156, v187
	s_waitcnt lgkmcnt(0)
	v_add_f32_e32 v157, v157, v188
	v_cndmask_b32_e64 v158, v156, v157, s[4:5]
	ds_bpermute_b32 v158, v179, v158
	v_pk_mul_f32 v[152:153], v[152:153], v[174:175] op_sel_hi:[1,0]
	v_pk_mul_f32 v[154:155], v[154:155], v[174:175] op_sel_hi:[1,0]
	v_cvt_pk_bf16_f32 v152, v152, v153
	v_cndmask_b32_e64 v153, v157, v156, s[4:5]
	s_waitcnt lgkmcnt(0)
	v_add_f32_e32 v156, v153, v158
	ds_bpermute_b32 v157, v180, v156
	v_cvt_pk_bf16_f32 v153, v154, v155
	global_store_dwordx2 v[168:169], v[152:153], off offset:512
	v_pk_mul_f32 v[148:149], v[148:149], v[174:175] op_sel_hi:[1,0]
	v_pk_mul_f32 v[150:151], v[150:151], v[174:175] op_sel_hi:[1,0]
	s_waitcnt lgkmcnt(0)
	v_add_f32_e32 v152, v156, v157
	ds_bpermute_b32 v153, v181, v152
	v_cvt_pk_bf16_f32 v148, v148, v149
	v_cvt_pk_bf16_f32 v149, v150, v151
	v_pk_mul_f32 v[150:151], v[144:145], v[174:175] op_sel_hi:[1,0]
	global_store_dwordx2 v[168:169], v[148:149], off offset:1024
	s_waitcnt lgkmcnt(0)
	v_add_f32_e32 v145, v152, v153
	ds_bpermute_b32 v148, v182, v145
	v_pk_mul_f32 v[146:147], v[146:147], v[174:175] op_sel_hi:[1,0]
	v_cvt_pk_bf16_f32 v150, v150, v151
	v_cvt_pk_bf16_f32 v151, v146, v147
	global_store_dwordx2 v[168:169], v[150:151], off offset:1536
	s_and_saveexec_b64 s[18:19], s[6:7]
	s_cbranch_execz .LBB0_86
	v_mov_b32_e32 v144, v204
	s_waitcnt lgkmcnt(0)
	v_add_f32_e32 v145, v145, v148
	v_ashrrev_i32_e32 v167, 31, v166
	v_fmac_f32_e32 v144, v174, v145
	s_and_saveexec_b64 s[20:21], s[8:9]
	s_xor_b64 s[20:21], exec, s[20:21]
	s_cbranch_execz .LBB0_92
; DI void prologue_phase(const Params& p, unsigned char* smem) {
;     ...
;                 else LF[r * 4 + gi - 4] = fminf(pre, 0.f) - log1pf(__expf(-fabsf(pre)));
	v_mul_f32_e64 v145, |v144|, s24
	v_exp_f32_e32 v158, v145
	v_max_f32_e32 v144, v144, v144
	v_min_f32_e32 v159, 0, v144
	v_add_f32_e32 v146, 1.0, v158
	v_add_f32_e32 v144, -1.0, v146
	v_sub_f32_e32 v145, v144, v146
	v_sub_f32_e32 v144, v158, v144
	v_add_f32_e32 v145, 1.0, v145
	v_add_f32_e32 v147, v144, v145
	v_frexp_mant_f32_e32 v148, v146
	v_cvt_f64_f32_e32 v[144:145], v146
	v_frexp_exp_i32_f64_e32 v144, v[144:145]
	v_cmp_gt_f32_e32 vcc, s25, v148
	s_nop 1
	v_subbrev_co_u32_e32 v152, vcc, 0, v144, vcc
	v_sub_u32_e32 v144, 0, v152
	v_ldexp_f32 v145, v146, v144
	v_add_f32_e32 v146, -1.0, v145
	v_add_f32_e32 v148, 1.0, v145
	v_ldexp_f32 v144, v147, v144
	v_add_f32_e32 v147, 1.0, v146
	v_add_f32_e32 v149, -1.0, v148
	v_sub_f32_e32 v147, v145, v147
	v_sub_f32_e32 v145, v145, v149
	v_add_f32_e32 v147, v144, v147
	v_add_f32_e32 v144, v144, v145
	v_add_f32_e32 v153, v148, v144
	v_rcp_f32_e32 v155, v153
	v_sub_f32_e32 v145, v153, v148
	v_sub_f32_e32 v154, v144, v145
	v_add_f32_e32 v145, v146, v147
	v_mul_f32_e32 v157, v145, v155
	v_sub_f32_e32 v144, v145, v146
	v_mul_f32_e32 v146, v153, v157
	v_fma_f32 v148, v157, v153, -v146
	v_fmac_f32_e32 v148, v157, v154
	v_sub_f32_e32 v156, v147, v144
	v_add_f32_e32 v144, v146, v148
	v_sub_f32_e32 v147, v145, v144
	v_pk_add_f32 v[150:151], v[144:145], v[146:147] neg_lo:[0,1] neg_hi:[0,1]
	v_mov_b32_e32 v149, v144
	v_pk_add_f32 v[144:145], v[150:151], v[148:149] neg_lo:[0,1] neg_hi:[0,1]
	v_cmp_neq_f32_e32 vcc, s27, v158
	v_add_f32_e32 v145, v156, v145
	v_add_f32_e32 v144, v144, v145
	v_add_f32_e32 v145, v147, v144
	v_mul_f32_e32 v156, v155, v145
	v_mul_f32_e32 v146, v153, v156
	v_fma_f32 v148, v156, v153, -v146
	v_fmac_f32_e32 v148, v156, v154
	v_sub_f32_e32 v147, v147, v145
	v_add_f32_e32 v153, v144, v147
	v_add_f32_e32 v144, v146, v148
	v_sub_f32_e32 v147, v145, v144
	v_pk_add_f32 v[150:151], v[144:145], v[146:147] neg_lo:[0,1] neg_hi:[0,1]
	v_mov_b32_e32 v149, v144
	v_pk_add_f32 v[144:145], v[150:151], v[148:149] neg_lo:[0,1] neg_hi:[0,1]
	s_nop 0
	v_add_f32_e32 v145, v153, v145
	v_add_f32_e32 v144, v144, v145
	v_add_f32_e32 v145, v157, v156
	v_add_f32_e32 v144, v147, v144
	v_sub_f32_e32 v146, v145, v157
	v_mul_f32_e32 v144, v155, v144
	v_sub_f32_e32 v146, v156, v146
	v_add_f32_e32 v146, v146, v144
	v_add_f32_e32 v148, v145, v146
	v_mul_f32_e32 v149, v148, v148
	v_fmamk_f32 v144, v149, 0x3e9b6dac, v183
	v_fmaak_f32 v173, v149, v144, 0x3f2aaada
	v_cvt_f32_i32_e32 v144, v152
	v_sub_f32_e32 v145, v148, v145
	v_sub_f32_e32 v145, v146, v145
	v_ldexp_f32 v150, v145, 1
	v_mul_f32_e32 v145, v148, v149
	v_ldexp_f32 v147, v148, 1
	v_pk_mul_f32 v[148:149], v[144:145], v[172:173]
	s_nop 0
	v_fma_f32 v146, v144, s26, -v148
	v_fmac_f32_e32 v146, 0xb102e308, v144
	v_pk_add_f32 v[144:145], v[148:149], v[146:147]
	s_nop 0
	v_sub_f32_e32 v147, v145, v147
	v_sub_f32_e32 v147, v149, v147
	v_add_f32_e32 v151, v150, v147
	v_mov_b32_e32 v150, v148
	v_pk_add_f32 v[148:149], v[144:145], v[148:149] neg_lo:[0,1] neg_hi:[0,1]
	v_pk_add_f32 v[152:153], v[144:145], v[150:151]
	v_mov_b32_e32 v147, v144
	v_mov_b32_e32 v149, v153
	v_pk_add_f32 v[154:155], v[146:147], v[148:149] neg_lo:[0,1] neg_hi:[0,1]
	v_pk_add_f32 v[146:147], v[146:147], v[148:149]
	v_mov_b32_e32 v150, v151
	v_pk_add_f32 v[148:149], v[146:147], v[144:145] op_sel:[1,0] op_sel_hi:[0,1] neg_lo:[0,1] neg_hi:[0,1]
	v_pk_add_f32 v[156:157], v[152:153], v[148:149] op_sel_hi:[1,0] neg_lo:[0,1] neg_hi:[0,1]
	v_mov_b32_e32 v152, v153
	v_mov_b32_e32 v153, v147
	v_pk_mov_b32 v[148:149], v[144:145], v[148:149] op_sel:[1,0]
	v_mov_b32_e32 v151, v144
	v_pk_add_f32 v[148:149], v[152:153], v[148:149] neg_lo:[0,1] neg_hi:[0,1]
	v_mov_b32_e32 v156, v154
	v_pk_add_f32 v[144:145], v[150:151], v[148:149] neg_lo:[0,1] neg_hi:[0,1]
	v_mov_b32_e32 v155, v147
	v_pk_add_f32 v[148:149], v[156:157], v[144:145]
	s_nop 0
	v_pk_add_f32 v[150:151], v[148:149], v[148:149] op_sel:[0,1] op_sel_hi:[1,0]
	s_nop 0
	v_pk_add_f32 v[146:147], v[146:147], v[150:151] op_sel:[1,0] op_sel_hi:[0,1]
	v_mov_b32_e32 v149, v146
	v_pk_add_f32 v[152:153], v[148:149], v[154:155] neg_lo:[0,1] neg_hi:[0,1]
	v_mov_b32_e32 v145, v150
	v_sub_f32_e32 v147, v148, v152
	v_pk_add_f32 v[144:145], v[144:145], v[152:153] neg_lo:[0,1] neg_hi:[0,1]
	v_sub_f32_e32 v147, v154, v147
	v_add_f32_e32 v144, v144, v147
	v_add_f32_e32 v144, v144, v145
	v_add_f32_e32 v144, v146, v144
	v_cndmask_b32_e32 v144, v184, v144, vcc
	v_cmp_ngt_f32_e32 vcc, -1.0, v158
	s_nop 1
	v_cndmask_b32_e32 v144, v185, v144, vcc
	v_cmp_neq_f32_e32 vcc, -1.0, v158
	s_nop 1
	v_cndmask_b32_e32 v144, v186, v144, vcc
	v_cmp_lt_f32_e64 vcc, |v158|, s28
	s_nop 1
	v_cndmask_b32_e32 v144, v144, v158, vcc
	v_sub_f32_e32 v146, v159, v144
	v_lshl_add_u64 v[144:145], v[166:167], 2, s[54:55]
	v_add_co_u32_e32 v144, vcc, 0x3900000, v144
	s_nop 1
	v_addc_co_u32_e32 v145, vcc, 0, v145, vcc
	global_store_dword v[144:145], v146, off offset:4080
